# nt cache policy also on the once-read K/V tile loads of the P2 chunk-state items
# speedup vs baseline: 1.0047x; 1.0040x over previous
; #define LAS __attribute__((address_space(3)))
; __device__ __forceinline__ void gla_gates(const Params& p, int l, int h, int tok0, int d, int tg, LAS float* gsum, float (&b)[16], float& blast) {
;     LAS float* lrs = gsum + 25088;
;     {
;         const int t2 = threadIdx.x;
;         if (t2 < 256) *(LAS f32x4*)(lrs + t2 * 4) = *(const f32x4*)((const float*)(p.ws + WS_ZLR) + (size_t)tok0 * 16 + t2 * 4);
;     }
; __device__ __forceinline__ void gla_local_item(const Params& p, int l, int c, int h, LAS unsigned char* lds) {
;     ...
;     const int lane = tid & 63, w = tid >> 6, fr = lane & 15, fq = lane >> 4, d = tid & 127, tg = tid >> 7;
;     unsigned char* ws = p.ws;
;     LAS float* gsum = (LAS float*)lds;
;     LAS float* decl = (LAS float*)(lds + 2048);
;     LAS unsigned char* kT = lds + 4096;
;     const int tok0 = c * 64;
;     const u16* kp = (const u16*)(ws + WS_ZK) + (size_t)(tok0 + tg * 16) * 512 + h * 128 + d;
;     u16 kraw[16];
; #pragma unroll
;     for (int i = 0; i < 16; ++i) kraw[i] = kp[i * 512];
;     const u16* vt = (const u16*)(ws + WS_ZVT) + (size_t)(h * 256 + w * 32 + fr) * T + tok0 + fq * 8;
;     bf16x8 bv[2][2];
; #pragma unroll
;     for (int kk = 0; kk < 2; ++kk)
; #pragma unroll
;         for (int n = 0; n < 2; ++n) bv[kk][n] = *(const bf16x8*)(vt + (size_t)(n * 16) * T + kk * 32);
.LBB0_503:
	v_mov_b32_e32 v30, v200
	s_and_b32 s1, s14, 0xffffffc
	v_ashrrev_i32_e32 v31, 7, v30
	v_add_lshl_u32 v18, v31, s1, 4
	v_ashrrev_i32_e32 v19, 31, v18
	v_and_b32_e32 v29, 0x7f, v30
	v_lshlrev_b64 v[2:3], 10, v[18:19]
	v_lshl_add_u64 v[2:3], s[40:41], 0, v[2:3]
	v_lshlrev_b32_e32 v0, 1, v29
	v_lshl_add_u64 v[2:3], v[2:3], 0, v[0:1]
	v_add_co_u32_e32 v4, vcc, s4, v2
	v_ashrrev_i32_e32 v0, 1, v30
	s_nop 0
	v_addc_co_u32_e32 v5, vcc, 0, v3, vcc
	v_add_co_u32_e32 v6, vcc, s92, v2
	v_and_b32_e32 v28, 0xffffffe0, v0
	s_nop 0
	v_addc_co_u32_e32 v7, vcc, 0, v3, vcc
	s_mov_b32 s0, s31
	v_add_co_u32_e32 v8, vcc, s5, v2
	v_and_b32_e32 v26, 15, v30
	v_add_u32_e32 v0, s29, v28
	s_and_b32 s18, s6, 0xffffffc0
	global_load_ushort v34, v[6:7], off offset:2048 nt
	global_load_ushort v32, v[6:7], off offset:3072 nt
	v_addc_co_u32_e32 v9, vcc, 0, v3, vcc
	global_load_ushort v46, v[2:3], off nt
	global_load_ushort v45, v[2:3], off offset:1024 nt
	global_load_ushort v44, v[2:3], off offset:2048 nt
	global_load_ushort v43, v[2:3], off offset:3072 nt
	global_load_ushort v40, v[4:5], off offset:1024 nt
	global_load_ushort v39, v[4:5], off offset:2048 nt
	global_load_ushort v38, v[4:5], off offset:3072 nt
	global_load_ushort v33, v[8:9], off nt
	v_or_b32_e32 v0, v0, v26
	v_mov_b64_e32 v[2:3], s[26:27]
	v_bfe_u32 v27, v30, 4, 2
	v_mad_i64_i32 v[2:3], s[10:11], v0, s96, v[2:3]
	s_ashr_i32 s19, s18, 31
	v_lshl_add_u64 v[2:3], s[18:19], 1, v[2:3]
	v_lshlrev_b32_e32 v0, 4, v27
	v_lshl_add_u64 v[2:3], v[2:3], 0, v[0:1]
	global_load_ushort v37, v[8:9], off offset:1024 nt
	global_load_ushort v36, v[8:9], off offset:2048 nt
	global_load_ushort v35, v[8:9], off offset:3072 nt
	global_load_dwordx4 v[10:13], v[2:3], off nt
	v_add_co_u32_e32 v8, vcc, 0x84000, v2
	s_nop 1
	v_addc_co_u32_e32 v9, vcc, 0, v3, vcc
	global_load_dwordx4 v[14:17], v[8:9], off nt
	s_nop 0
	global_load_dwordx4 v[2:5], v[2:3], off offset:64 nt
	s_nop 0
	global_load_ushort v47, v[6:7], off offset:-4096 nt
	global_load_ushort v42, v[6:7], off nt
	global_load_ushort v41, v[6:7], off offset:1024 nt
	s_nop 0
	global_load_dwordx4 v[6:9], v[8:9], off offset:64 nt
	s_and_saveexec_b64 s[20:21], s[36:37]
	s_cbranch_execz .LBB0_505
	s_lshl_b64 s[10:11], s[18:19], 6
	v_lshl_add_u64 v[66:67], v[138:139], 0, s[10:11]
	global_load_dwordx4 v[66:69], v[66:67], off
